# speedup vs baseline: 1.0075x; 1.0075x over previous
; #define PH(k) if (((PHMASK >> (k)) & 1) && P.ph_lo <= (k) && (k) < P.ph_hi)
; #define SYNC(k) do { if ((k) + 1 < P.ph_hi) { if ((k) == 0) grid.sync(); else xcd_barrier(xb); } } while (0)
; #define REP(b) for (int _rep = 0; _rep < (((REPMASK >> (b)) & 1) ? 2 : 1); ++_rep)
; __global__ __launch_bounds__(512, 2) void mega(Params P) {
;     ...
;         PH(2) { REP(1) phase_na(P, shm); REP(2) phase_lru<1>(P, shm); SYNC(2); }
.LBB0_203:
	s_setprio 0
	s_add_u32 s40, s90, 0x16000000
	s_addc_u32 s41, s91, 0
	s_cmp_lt_i32 s92, 3
	s_cselect_b64 s[0:1], -1, 0
	s_cmp_gt_i32 s93, 2
	s_cselect_b64 s[4:5], -1, 0
	s_and_b64 s[0:1], s[0:1], s[4:5]
	s_andn2_b64 vcc, exec, s[0:1]
	s_cbranch_vccnz .LBB0_434
	s_mov_b32 s98, 0
	s_bitcmp1_b32 s2, 7
	s_cbranch_scc0 .Lna_start
	s_mov_b32 s98, 1
	s_and_b32 s3, s2, 7
	s_lshl_b32 s24, s3, 7
	v_bfe_u32 v65, v144, 4, 2
	v_and_b32_e32 v64, 15, v144
	v_lshlrev_b32_e32 v68, 3, v65
	v_lshlrev_b32_e32 v69, 2, v65
	v_lshlrev_b32_e32 v66, 4, v65
	v_mov_b32_e32 v67, 0
	v_mov_b32_e32 v71, 0
	s_mov_b64 s[4:5], 0
	s_branch .LBB0_338
